# prompt attention: K/V tile prefetch distance 2 (wave groups alternate as loader/writer)
# speedup vs baseline: 1.0238x; 1.0056x over previous
; #define LAS __attribute__((address_space(3)))
; __device__ __forceinline__ u32x4 pack8(f32x4 a, f32x4 b) { u32x4 w; w.x = cvt_pk_bf16(a[0], a[1]); w.y = cvt_pk_bf16(a[2], a[3]); w.z = cvt_pk_bf16(b[0], b[1]); w.w = cvt_pk_bf16(b[2], b[3]); return w; }
; __device__ __forceinline__ void attn_unit(const Args& a, LAS unsigned char* lds, const int mode, const int h, const int qb, const int tid_in, const int lane_in, const int wave) {
;     ...
;     auto tile_write = [&](int j, int buf) {
;         u32x4 kw, vw;
;         if (mode == 1 && j < 32) { kw = pack8(kst[0], kst[1]); vw = pack8(vst[0], vst[1]); }
;         else { kw = __builtin_bit_cast(u32x4, kst[0]); vw = __builtin_bit_cast(u32x4, vst[0]); }
;         *(LAS u32x4*)(lds + AT_K + buf * AT_KB + sr * 144 + sc8 * 16) = kw;
;         *(LAS u32x4*)(lds + AT_V + buf * AT_VB + sr * 160 + sc8 * 16) = vw;
;         if (tid < 64) *(LAS float*)(lds + AT_CK + buf * 256 + tid * 4) = ckst;
;     };
;     float m_run = -INFINITY, l_run = 0.f, cqm = 0.f; f32x16 o0 = {}, o1 = {};
;     ...
;     tile_load(jstart); tile_write(jstart, 0); __syncthreads();
;     for (int j = jstart; j < NT; ++j) {
;         const int buf = (j - jstart) & 1;
;         if (j + 1 < NT) tile_load(j + 1);
.LBB0_516:
	s_or_b64 exec, exec, s[0:1]
	v_mul_lo_u32 v5, v2, s25
	v_lshlrev_b32_e32 v4, 4, v4
	v_add3_u32 v91, 0, v5, v4
	v_lshl_add_u32 v95, v2, 4, v91
	v_lshl_add_u32 v96, v1, 2, 0
	s_waitcnt vmcnt(1)
	ds_write_b128 v91, v[82:85]
	s_waitcnt vmcnt(0)
	ds_write_b128 v95, v[86:89] offset:18432
	s_and_saveexec_b64 s[0:1], s[2:3]
	ds_write_b32 v96, v97 offset:38912
	s_or_b64 exec, exec, s[0:1]
	s_add_i32 s16, s16, 4
	s_cmp_ge_i32 s12, s16
	s_waitcnt lgkmcnt(0)
	s_barrier
	s_cbranch_scc1 .LBB0_539
	v_add_f32_e32 v4, v9, v10
	v_or_b32_e32 v94, s14, v3
	v_lshlrev_b32_e32 v102, 2, v7
	v_lshrrev_b32_e32 v3, 2, v1
	v_mul_f32_e32 v100, 0x3fb8aa3b, v4
	v_and_or_b32 v3, v3, 3, v102
	s_movk_i32 s0, 0xa0
	v_lshlrev_b32_e32 v4, 1, v8
	v_lshlrev_b32_e32 v5, 3, v8
	v_lshl_add_u32 v98, v7, 4, 0
	v_mad_u32_u24 v3, v3, s0, 0
	v_and_b32_e32 v4, 32, v4
	v_and_b32_e32 v5, 24, v5
	v_mov_b32_e32 v14, v0
	v_mov_b32_e32 v15, v0
	v_sub_u32_e32 v99, v92, v6
	v_add3_u32 v104, v3, v4, v5
	v_mad_u32_u24 v105, v6, s25, v98
	v_add_u32_e32 v106, 64, v1
	v_add_u32_e32 v107, 64, v2
	v_mov_b32_e32 v1, v0
	v_mov_b32_e32 v2, v0
	v_mov_b32_e32 v3, v0
	v_mov_b32_e32 v4, v0
	v_mov_b32_e32 v5, v0
	v_mov_b32_e32 v6, v0
	v_mov_b32_e32 v7, v0
	v_mov_b32_e32 v8, v0
	v_mov_b32_e32 v9, v0
	v_mov_b32_e32 v10, v0
	v_mov_b32_e32 v11, v0
	v_mov_b32_e32 v12, v0
	v_mov_b32_e32 v13, v0
	v_mov_b64_e32 v[32:33], v[14:15]
	s_add_i32 s15, s12, s15
	v_mov_b64_e32 v[30:31], v[12:13]
	v_mov_b64_e32 v[28:29], v[10:11]
	v_mov_b64_e32 v[26:27], v[8:9]
	v_mov_b64_e32 v[24:25], v[6:7]
	v_mov_b64_e32 v[22:23], v[4:5]
	v_mov_b64_e32 v[20:21], v[2:3]
	v_mov_b64_e32 v[18:19], v[0:1]
	v_mov_b64_e32 v[16:17], v[14:15]
	v_add_u32_e32 v101, 31, v99
	s_add_i32 s15, s15, 1
	s_mov_b32 s17, 0
	v_mov_b32_e32 v108, 0xff800000
	v_mov_b32_e32 v103, 0
	v_mov_b64_e32 v[14:15], v[12:13]
	v_mov_b64_e32 v[12:13], v[10:11]
	v_mov_b64_e32 v[10:11], v[8:9]
	v_mov_b64_e32 v[8:9], v[6:7]
	v_mov_b64_e32 v[6:7], v[4:5]
	v_mov_b64_e32 v[4:5], v[2:3]
	v_mov_b64_e32 v[2:3], v[0:1]
	v_mov_b32_e32 v1, 0
	v_readlane_b32 s98, v254, 21
	s_nop 3
	s_lshr_b32 s98, s98, 2
	s_mul_i32 s101, s98, 0x1200
	v_subrev_u32_e32 v156, s101, v91
	s_mul_i32 s101, s98, 0x1400
	v_subrev_u32_e32 v157, s101, v95
	s_lshl_b32 s101, s98, 5
	v_subrev_u32_e32 v158, s101, v107
	v_add_u32_e32 v158, 64, v158
	s_mov_b32 s99, 0
	s_cmp_eq_u32 s98, 0
	s_cbranch_scc1 .Lpa_pre_done
	s_add_i32 s100, s12, 1
	s_cmp_ge_i32 s100, s16
	s_cbranch_scc1 .Lpa_pre_done
	v_add_u32_e32 v34, s13, v158
	v_add_u32_e32 v34, 0xffffffc0, v34
	v_ashrrev_i32_e32 v35, 31, v34
	v_lshlrev_b64 v[34:35], 11, v[34:35]
	v_lshl_or_b32 v34, v94, 1, v34
	v_lshl_add_u64 v[36:37], s[38:39], 0, v[34:35]
	v_lshl_add_u64 v[34:35], s[40:41], 0, v[34:35]
	s_mov_b64 s[100:101], 0x10000
	global_load_dwordx4 v[140:143], v[36:37], off
	global_load_dwordx4 v[148:151], v[34:35], off
	v_lshl_add_u64 v[36:37], v[36:37], 0, s[100:101]
	v_lshl_add_u64 v[34:35], v[34:35], 0, s[100:101]
	global_load_dwordx4 v[144:147], v[36:37], off
	global_load_dwordx4 v[152:155], v[34:35], off
.Lpa_pre_done:
	s_branch .LBB0_522
.LBB0_520:
	s_or_b64 exec, exec, s[0:1]

; __device__ __forceinline__ void attn_unit(const Args& a, LAS unsigned char* lds, const int mode, const int h, const int qb, const int tid_in, const int lane_in, const int wave) {
;     ...
;         } else {
;             const int krow = mode == 0 ? j * 64 : MP + qb * 64;
;             const size_t off = (size_t)(krow + sr) * D + h * HD + sc8 * 8;
;             kst[0] = *(const f32x4*)(Kb + off); vst[0] = *(const f32x4*)(Vb + off);
;             if (tid < 64) { const float pfx = mode == 0 ? ((const float*)(ws + WS_PFXP))[h * 256 + j] : ((const float*)(ws + WS_PFXS))[qb * 16 + h];
;                 ckst = (pfx + CLT[krow + tid]) * L2E; }
;         }
;     ...
;     for (int j = jstart; j < NT; ++j) {
;         const int buf = (j - jstart) & 1;
;         if (j + 1 < NT) tile_load(j + 1);
.LBB0_522:
	s_add_i32 s0, s12, s17
	s_add_i32 s0, s0, 1
	s_cmp_lt_i32 s0, s16
	s_cselect_b64 s[4:5], -1, 0
	s_cmp_ge_i32 s0, s16
	s_cbranch_scc1 .LBB0_526
	s_and_saveexec_b64 s[0:1], s[2:3]
	s_cbranch_execz .Lpa_nock
	s_add_i32 s6, s15, s17
	s_ashr_i32 s7, s6, 31
	v_add_u32_e32 v34, s13, v106
	s_lshl_b64 s[6:7], s[6:7], 2
	v_ashrrev_i32_e32 v35, 31, v34
	s_add_u32 s6, s60, s6
	v_lshl_add_u64 v[34:35], v[34:35], 2, s[8:9]
	s_addc_u32 s7, s61, s7
	global_load_dword v194, v0, s[6:7]
	s_nop 0
	global_load_dword v195, v[34:35], off
.Lpa_nock:
	s_or_b64 exec, exec, s[0:1]
	s_mov_b32 s99, 0
	s_and_b32 s100, s17, 1
	s_cmp_lg_u32 s100, s98
	s_cbranch_scc1 .LBB0_526
	s_add_i32 s100, s12, s17
	s_add_i32 s100, s100, 2
	s_cmp_ge_i32 s100, s16
	s_cbranch_scc1 .LBB0_526
	s_mov_b32 s99, 1
	v_add_u32_e32 v34, s13, v158
	v_ashrrev_i32_e32 v35, 31, v34
	v_lshlrev_b64 v[34:35], 11, v[34:35]
	v_lshl_or_b32 v34, v94, 1, v34
	v_lshl_add_u64 v[36:37], s[38:39], 0, v[34:35]
	v_lshl_add_u64 v[34:35], s[40:41], 0, v[34:35]
	s_mov_b64 s[100:101], 0x10000
	global_load_dwordx4 v[140:143], v[36:37], off
	global_load_dwordx4 v[148:151], v[34:35], off
	v_lshl_add_u64 v[36:37], v[36:37], 0, s[100:101]
	v_lshl_add_u64 v[34:35], v[34:35], 0, s[100:101]
	global_load_dwordx4 v[144:147], v[36:37], off
	global_load_dwordx4 v[152:155], v[34:35], off

; #define LAS __attribute__((address_space(3)))
; __device__ __forceinline__ u32x4 pack8(f32x4 a, f32x4 b) { u32x4 w; w.x = cvt_pk_bf16(a[0], a[1]); w.y = cvt_pk_bf16(a[2], a[3]); w.z = cvt_pk_bf16(b[0], b[1]); w.w = cvt_pk_bf16(b[2], b[3]); return w; }
; __device__ __forceinline__ void attn_unit(const Args& a, LAS unsigned char* lds, const int mode, const int h, const int qb, const int tid_in, const int lane_in, const int wave) {
;     ...
;     auto tile_write = [&](int j, int buf) {
;         u32x4 kw, vw;
;         if (mode == 1 && j < 32) { kw = pack8(kst[0], kst[1]); vw = pack8(vst[0], vst[1]); }
;         else { kw = __builtin_bit_cast(u32x4, kst[0]); vw = __builtin_bit_cast(u32x4, vst[0]); }
;         *(LAS u32x4*)(lds + AT_K + buf * AT_KB + sr * 144 + sc8 * 16) = kw;
;         *(LAS u32x4*)(lds + AT_V + buf * AT_VB + sr * 160 + sc8 * 16) = vw;
;         if (tid < 64) *(LAS float*)(lds + AT_CK + buf * 256 + tid * 4) = ckst;
;     ...
;         if (j + 1 < NT) tile_write(j + 1, buf ^ 1);
;         __syncthreads();
.LBB0_536:
	s_or_b64 exec, exec, s[6:7]
	s_andn2_b64 vcc, exec, s[4:5]
	s_cbranch_vccnz .LBB0_521
	s_xor_b32 s4, s18, 1
	s_and_b32 s100, s17, 1
	s_cmp_eq_u32 s100, s98
	s_cbranch_scc1 .Lpa_notwriter
	s_mul_i32 s0, s4, 0x2400
	v_add_u32_e32 v34, s0, v156
	s_mul_i32 s0, s4, 0x2800
	v_add_u32_e32 v35, s0, v157
	s_waitcnt vmcnt(0)
	ds_write_b128 v34, v[140:143]
	ds_write_b128 v34, v[144:147] offset:4608
	ds_write_b128 v35, v[148:151] offset:18432
	ds_write_b128 v35, v[152:155] offset:23552
	s_branch .Lpa_ck
.Lpa_notwriter:
	s_cmp_eq_u32 s99, 1
	s_cbranch_scc1 .Lpa_w4
	s_waitcnt vmcnt(0)
	s_branch .Lpa_ck
.Lpa_w4:
	s_waitcnt vmcnt(4)
.Lpa_ck:
	s_and_saveexec_b64 s[0:1], s[2:3]
	s_cbranch_execz .LBB0_520
	v_lshl_add_u32 v34, s4, 8, v96
	v_add_f32_e32 v97, v194, v195
	v_mul_f32_e32 v97, 0x3fb8aa3b, v97
	ds_write_b32 v34, v97 offset:38912
	s_branch .LBB0_520

; __global__ void __launch_bounds__(512, 2) fwd_megakernel(Args a) {
	.amdhsa_kernel _Z14fwd_megakernel4Args
		.amdhsa_group_segment_fixed_size 0
		.amdhsa_private_segment_fixed_size 0
		.amdhsa_kernarg_size 480
		.amdhsa_user_sgpr_count 2
		.amdhsa_user_sgpr_dispatch_ptr 0
		.amdhsa_user_sgpr_queue_ptr 0
		.amdhsa_user_sgpr_kernarg_segment_ptr 1
		.amdhsa_user_sgpr_dispatch_id 0
		.amdhsa_user_sgpr_kernarg_preload_length 0
		.amdhsa_user_sgpr_kernarg_preload_offset 0
		.amdhsa_user_sgpr_private_segment_size 0
		.amdhsa_uses_dynamic_stack 0
		.amdhsa_enable_private_segment 0
		.amdhsa_system_sgpr_workgroup_id_x 1
		.amdhsa_system_sgpr_workgroup_id_y 0
		.amdhsa_system_sgpr_workgroup_id_z 0
		.amdhsa_system_sgpr_workgroup_info 0
		.amdhsa_system_vgpr_workitem_id 2
		.amdhsa_next_free_vgpr 256
		.amdhsa_next_free_sgpr 102
		.amdhsa_accum_offset 256
		.amdhsa_reserve_vcc 1
		.amdhsa_float_round_mode_32 0
		.amdhsa_float_round_mode_16_64 0
		.amdhsa_float_denorm_mode_32 3
		.amdhsa_float_denorm_mode_16_64 3
		.amdhsa_dx10_clamp 1
		.amdhsa_ieee_mode 1
		.amdhsa_fp16_overflow 0
		.amdhsa_tg_split 0
		.amdhsa_exception_fp_ieee_invalid_op 0
		.amdhsa_exception_fp_denorm_src 0
		.amdhsa_exception_fp_ieee_div_zero 0
		.amdhsa_exception_fp_ieee_overflow 0
		.amdhsa_exception_fp_ieee_underflow 0
		.amdhsa_exception_fp_ieee_inexact 0
		.amdhsa_exception_int_div_zero 0
	.end_amdhsa_kernel

; __global__ void __launch_bounds__(512, 2) fwd_megakernel(Args a) {
amdhsa.kernels:
  - .agpr_count:     0
    .args:
      - .offset:         0
        .size:           224
        .value_kind:     by_value
      - .offset:         224
        .size:           4
        .value_kind:     hidden_block_count_x
      - .offset:         228
        .size:           4
        .value_kind:     hidden_block_count_y
      - .offset:         232
        .size:           4
        .value_kind:     hidden_block_count_z
      - .offset:         236
        .size:           2
        .value_kind:     hidden_group_size_x
      - .offset:         238
        .size:           2
        .value_kind:     hidden_group_size_y
      - .offset:         240
        .size:           2
        .value_kind:     hidden_group_size_z
      - .offset:         242
        .size:           2
        .value_kind:     hidden_remainder_x
      - .offset:         244
        .size:           2
        .value_kind:     hidden_remainder_y
      - .offset:         246
        .size:           2
        .value_kind:     hidden_remainder_z
      - .offset:         264
        .size:           8
        .value_kind:     hidden_global_offset_x
      - .offset:         272
        .size:           8
        .value_kind:     hidden_global_offset_y
      - .offset:         280
        .size:           8
        .value_kind:     hidden_global_offset_z
      - .offset:         288
        .size:           2
        .value_kind:     hidden_grid_dims
      - .offset:         312
        .size:           8
        .value_kind:     hidden_multigrid_sync_arg
      - .offset:         344
        .size:           4
        .value_kind:     hidden_dynamic_lds_size
    .group_segment_fixed_size: 0
    .kernarg_segment_align: 8
    .kernarg_segment_size: 480
    .language:       OpenCL C
    .language_version:
      - 2
      - 0
    .max_flat_workgroup_size: 512
    .name:           _Z14fwd_megakernel4Args
    .private_segment_fixed_size: 0
    .sgpr_count:     108
    .sgpr_spill_count: 80
    .symbol:         _Z14fwd_megakernel4Args.kd
    .uniform_work_group_size: 1
    .uses_dynamic_stack: false
    .vgpr_count:     256
    .vgpr_spill_count: 0
    .wavefront_size: 64
